# DSA batch loop: head select by 3 v_cndmask with SGPR lane masks (was nested EXEC diamond), plain v_rsq for per-key rstd (input >= eps, never denormal), dead xors removed
# speedup vs baseline: 1.0057x; 1.0057x over previous
; #define LAS __attribute__((address_space(3)))
;     ...
;       bf16x8 qa[4];
;       { const u16* qp = prow + qgrow * NP + C_QL + (c16 & 3) * 128 + quad * 8;
; #pragma unroll
;         for (int ks = 0; ks < 4; ++ks) qa[ks] = *(const bf16x8*)(qp + ks * 32); }
;       f32x4 oacc[8];
; #pragma unroll
;       for (int c = 0; c < 8; ++c) oacc[c] = (f32x4){0.f, 0.f, 0.f, 0.f};
;       const unsigned fsw = ((c16 & 3) << 2) | (c16 >> 2);
;       const unsigned wb = (unsigned)(unsigned long long)wbase;
;       unsigned tra[8][2];
;       { const unsigned q4 = c16 >> 2, p4 = c16 & 3;
; #pragma unroll
;         for (int t = 0; t < 2; ++t) { const unsigned fv = (q4 << 2) | ((2 * quad + t) & 3), rowb = wb + (8 * quad + 4 * t + q4) * 256 + 8 * (p4 & 1);
; #pragma unroll
;             for (int c = 0; c < 8; ++c) tra[c][t] = rowb + 16 * ((2 * c + (p4 >> 1)) ^ fv); } }
;       LAS u16* pbT = (LAS u16*)pbuf;
;       float mrun = -1e30f, lsum = 0.f;
;       const int nb = (sm & 8) ? ((kcount + 63) >> 6) : 0;
;       u32x4 w[4][4];
;       auto gl = [&](int b) {
; #pragma unroll
;           for (int jj = 0; jj < 4; ++jj) { const int kx = list[(b * 4 + jj) * 16 + c16] & 4095; const u16* cp = prow + (size_t)kx * NP + C_BC + quad * 8;
; #pragma unroll
;               for (int ks = 0; ks < 4; ++ks) w[jj][ks] = *(const u32x4*)(cp + ks * 32); } };
;       if (nb > 0) gl(0);
.LBB0_926:
	v_lshrrev_b32_e32 v128, 4, v163
	v_and_b32_e32 v127, 15, v174
	v_lshlrev_b32_e32 v18, 3, v128
	v_mov_b32_e32 v109, 0
	s_andn2_b64 vcc, exec, s[0:1]
	v_and_b32_e32 v126, 48, v174
	v_lshlrev_b32_e32 v124, 1, v18
	v_cmp_eq_u32_e64 s[38:39], 0, v127
	v_lshl_add_u32 v129, v128, 2, s56
	v_mov_b32_e32 v108, v109
	v_mov_b32_e32 v107, v109
	v_mov_b32_e32 v106, v109
	v_mov_b32_e32 v113, v109
	v_mov_b32_e32 v112, v109
	v_mov_b32_e32 v111, v109
	v_mov_b32_e32 v110, v109
	v_mov_b32_e32 v93, v109
	v_mov_b32_e32 v92, v109
	v_mov_b32_e32 v91, v109
	v_mov_b32_e32 v90, v109
	v_mov_b32_e32 v85, v109
	v_mov_b32_e32 v84, v109
	v_mov_b32_e32 v83, v109
	v_mov_b32_e32 v82, v109
	v_mov_b32_e32 v89, v109
	v_mov_b32_e32 v88, v109
	v_mov_b32_e32 v87, v109
	v_mov_b32_e32 v86, v109
	v_mov_b32_e32 v97, v109
	v_mov_b32_e32 v96, v109
	v_mov_b32_e32 v95, v109
	v_mov_b32_e32 v94, v109
	v_mov_b32_e32 v105, v109
	v_mov_b32_e32 v104, v109
	v_mov_b32_e32 v103, v109
	v_mov_b32_e32 v102, v109
	v_mov_b32_e32 v101, v109
	v_mov_b32_e32 v100, v109
	v_mov_b32_e32 v99, v109
	v_mov_b32_e32 v98, v109
	v_mov_b32_e32 v118, v109
	s_cbranch_vccnz .LBB0_953
	s_mul_hi_i32 s1, s61, 0x5800
	s_mulk_i32 s61, 0x5800
	v_lshlrev_b32_e32 v0, 7, v127
	s_add_u32 s0, s54, s61
	v_and_b32_e32 v82, 0x180, v0
	s_addc_u32 s1, s55, s1
	v_lshlrev_b32_e32 v0, 1, v82
	v_lshl_add_u64 v[2:3], s[0:1], 0, v[0:1]
	v_lshrrev_b32_e32 v83, 2, v127
	v_lshlrev_b32_e32 v0, 1, v128
	v_and_b32_e32 v84, 12, v174
	v_and_b32_e32 v85, 2, v0
	v_or_b32_e32 v0, v18, v83
	v_lshlrev_b32_e32 v18, 3, v127
	v_or_b32_e32 v86, v85, v84
	v_bfe_u32 v19, v174, 1, 1
	v_and_or_b32 v18, v18, 8, s60
	v_mov_b32_e32 v125, v1
	v_lshl_add_u32 v88, v0, 8, v18
	v_or_b32_e32 v0, v86, v19
	v_or_b32_e32 v89, 2, v19
	v_lshlrev_b32_e32 v95, 1, v127
	v_lshl_add_u64 v[14:15], v[2:3], 0, v[124:125]
	v_lshl_add_u32 v130, v0, 4, v88
	v_bitop3_b32 v0, v85, v89, v84 bitop3:0x36
	v_or_b32_e32 v90, 4, v19
	v_add_u32_e32 v96, s56, v95
	global_load_dwordx4 v[2:5], v[14:15], off offset:3072
	global_load_dwordx4 v[6:9], v[14:15], off offset:3136
	global_load_dwordx4 v[10:13], v[14:15], off offset:3200
	s_nop 0
	global_load_dwordx4 v[14:17], v[14:15], off offset:3264
	v_lshl_add_u32 v131, v0, 4, v88
	v_bitop3_b32 v0, v85, v90, v84 bitop3:0x36
	v_or_b32_e32 v91, 6, v19
	ds_read_u16 v18, v96
	ds_read_u16 v20, v96 offset:32
	v_lshl_add_u32 v132, v0, 4, v88
	v_bitop3_b32 v0, v85, v91, v84 bitop3:0x36
	v_or_b32_e32 v92, 8, v19
	v_lshl_add_u32 v133, v0, 4, v88
	v_bitop3_b32 v0, v85, v92, v84 bitop3:0x36
	v_or_b32_e32 v93, 10, v19
	v_lshl_add_u32 v134, v0, 4, v88
	v_bitop3_b32 v0, v85, v93, v84 bitop3:0x36
	v_or_b32_e32 v94, 12, v19
	v_lshl_add_u32 v135, v0, 4, v88
	v_bitop3_b32 v0, v85, v94, v84 bitop3:0x36
	ds_read_u16 v50, v96 offset:64
	ds_read_u16 v51, v96 offset:96
	s_mov_b32 s1, 0x5040100
	v_lshl_add_u32 v136, v0, 4, v88
	s_waitcnt lgkmcnt(2)
	v_perm_b32 v0, v20, v18, s1
	s_movk_i32 s20, 0xfff
	v_and_b32_e32 v18, 0xfff0fff, v0
	v_bitop3_b32 v0, v0, s20, v207 bitop3:0x80
	v_mul_u32_u24_e32 v0, 0x5800, v0
	v_or_b32_e32 v97, 14, v19
	v_mul_u32_u24_sdwa v34, v18, s33 dst_sel:DWORD dst_unused:UNUSED_PAD src0_sel:WORD_1 src1_sel:DWORD
	v_lshl_add_u64 v[18:19], s[54:55], 0, v[0:1]
	v_lshl_add_u64 v[18:19], v[18:19], 0, v[124:125]
	s_movk_i32 s0, 0x1000
	v_mov_b32_e32 v35, v1
	s_waitcnt lgkmcnt(0)
	v_perm_b32 v0, v51, v50, s1
	v_add_co_u32_e32 v26, vcc, s0, v18
	v_lshl_add_u64 v[34:35], s[54:55], 0, v[34:35]
	v_and_b32_e32 v50, 0xfff0fff, v0
	v_bitop3_b32 v0, v0, s20, v207 bitop3:0x80
	v_addc_co_u32_e32 v27, vcc, 0, v19, vcc
	v_lshl_add_u64 v[34:35], v[34:35], 0, v[124:125]
	v_mul_u32_u24_e32 v0, 0x5800, v0
	v_add_co_u32_e32 v42, vcc, s0, v34
	v_mul_u32_u24_sdwa v66, v50, s33 dst_sel:DWORD dst_unused:UNUSED_PAD src0_sel:WORD_1 src1_sel:DWORD
	v_lshl_add_u64 v[50:51], s[54:55], 0, v[0:1]
	v_addc_co_u32_e32 v43, vcc, 0, v35, vcc
	v_lshl_add_u64 v[50:51], v[50:51], 0, v[124:125]
	v_mov_b32_e32 v67, v1
	v_add_co_u32_e32 v58, vcc, s0, v50
	v_lshl_add_u64 v[66:67], s[54:55], 0, v[66:67]
	s_nop 0
	v_addc_co_u32_e32 v59, vcc, 0, v51, vcc
	v_lshl_add_u64 v[66:67], v[66:67], 0, v[124:125]
	s_mov_b64 s[24:25], 0x1000
	v_add_co_u32_e32 v74, vcc, s0, v66
	v_lshl_add_u64 v[30:31], v[18:19], 0, s[24:25]
	v_lshl_add_u64 v[46:47], v[34:35], 0, s[24:25]
	v_lshl_add_u64 v[62:63], v[50:51], 0, s[24:25]
	v_lshl_add_u64 v[78:79], v[66:67], 0, s[24:25]
	v_addc_co_u32_e32 v75, vcc, 0, v67, vcc
	global_load_dwordx4 v[18:21], v[30:31], off offset:64
	global_load_dwordx4 v[22:25], v[30:31], off offset:128
	s_nop 0
	global_load_dwordx4 v[26:29], v[26:27], off
	s_nop 0
	global_load_dwordx4 v[30:33], v[30:31], off offset:192
	s_nop 0
	global_load_dwordx4 v[34:37], v[46:47], off offset:64
	global_load_dwordx4 v[38:41], v[46:47], off offset:128
	s_nop 0
	global_load_dwordx4 v[42:45], v[42:43], off
	s_nop 0
	global_load_dwordx4 v[46:49], v[46:47], off offset:192
	s_nop 0
	global_load_dwordx4 v[50:53], v[62:63], off offset:64
	global_load_dwordx4 v[54:57], v[62:63], off offset:128
	s_nop 0
	global_load_dwordx4 v[58:61], v[58:59], off
	s_nop 0
	global_load_dwordx4 v[62:65], v[62:63], off offset:192
	s_nop 0
	global_load_dwordx4 v[66:69], v[78:79], off offset:64
	global_load_dwordx4 v[70:73], v[78:79], off offset:128
	s_nop 0
	global_load_dwordx4 v[74:77], v[74:75], off
	s_nop 0
	global_load_dwordx4 v[78:81], v[78:79], off offset:192
	v_lshrrev_b32_e32 v87, 1, v174
	v_bitop3_b32 v0, v85, v97, v84 bitop3:0x36
	v_lshl_add_u32 v137, v0, 4, v88
	v_add_u32_e32 v0, 0x400, v88
	v_bitop3_b32 v84, v86, v87, 1 bitop3:0x72
	v_lshl_add_u32 v138, v84, 4, v0
	v_bitop3_b32 v84, v86, v89, 1 bitop3:0x36
; #define LAS __attribute__((address_space(3)))
;     ...
;       for (int b = 0; b < nb; ++b) {
;           float lgv[4], rsv[4];
; #pragma unroll
;           for (int jj = 0; jj < 4; ++jj) {
;               const int rho = jj * 16 + c16, slot = b * 64 + rho;
;               f32x4 a = {0.f, 0.f, 0.f, 0.f}; float ss = 0.f;
; #pragma unroll
;               for (int ks = 0; ks < 4; ++ks) {
; #pragma unroll
;                   for (int e = 0; e < 4; ++e) asm("v_dot2_f32_bf16 %0, %1, %1, %0" : "+v"(ss) : "v"(w[jj][ks][e]));
;                   a = __builtin_amdgcn_mfma_f32_16x16x32_bf16(qa[ks], *reinterpret_cast<const bf16x8*>(&w[jj][ks]), a, 0, 0, 0);
;                   *(LAS u32x4*)(wbase + rho * 256 + (((ks * 4 + quad) ^ fsw) << 4)) = w[jj][ks]; }
;               ss += __shfl_xor(ss, 16); ss += __shfl_xor(ss, 32);
;               const float rstd = rsqrtf(ss * (1.f / 128.f) + EPS);
;               const float av = quad == 0 ? a[0] : (quad == 1 ? a[1] : (quad == 2 ? a[2] : a[3]));
	v_lshl_add_u32 v139, v84, 4, v0
	v_bitop3_b32 v84, v86, v90, 1 bitop3:0x36
	v_lshl_add_u32 v140, v84, 4, v0
	v_bitop3_b32 v84, v86, v91, 1 bitop3:0x36
	v_lshl_add_u32 v141, v84, 4, v0
	v_bitop3_b32 v84, v86, v92, 1 bitop3:0x36
	v_lshl_add_u32 v142, v84, 4, v0
	v_bitop3_b32 v84, v86, v93, 1 bitop3:0x36
	v_lshl_add_u32 v143, v84, 4, v0
	v_bitop3_b32 v84, v86, v94, 1 bitop3:0x36
	v_lshl_add_u32 v144, v84, 4, v0
	v_bitop3_b32 v84, v86, v97, 1 bitop3:0x36
	v_lshl_add_u32 v145, v84, 4, v0
	v_lshlrev_b32_e32 v0, 2, v127
	v_and_b32_e32 v0, 12, v0
	v_bitop3_b32 v85, v0, v128, v83 bitop3:0x36
	v_lshlrev_b32_e32 v147, 4, v85
	v_or_b32_e32 v85, 4, v128
	v_bitop3_b32 v85, v0, v85, v83 bitop3:0x36
	v_lshlrev_b32_e32 v148, 4, v85
	v_or_b32_e32 v85, 8, v128
	v_bitop3_b32 v85, v0, v85, v83 bitop3:0x36
	v_lshlrev_b32_e32 v149, 4, v85
	v_or_b32_e32 v85, 12, v128
	v_lshlrev_b32_e32 v84, 7, v128
	v_add_u32_e32 v82, s56, v82
	v_lshl_add_u32 v146, v127, 8, s60
	v_bitop3_b32 v0, v0, v85, v83 bitop3:0x36
	s_add_i32 s57, s57, 0x20080
	v_mov_b32_e32 v159, 0
	s_mov_b32 s24, 0
	v_cmp_eq_u32_e64 s[40:41], 2, v128
	v_cmp_eq_u32_e64 s[66:67], 1, v128
	v_cmp_eq_u32_e64 s[68:69], 3, v128
	v_lshlrev_b32_e32 v150, 4, v0
	v_add_u32_e32 v151, 0x1000, v146
	v_add_u32_e32 v152, 0x2000, v146
	v_add_u32_e32 v153, 0x3000, v146
	v_add_u32_e32 v154, s57, v95
	v_mov_b32_e32 v160, 0xf149f2ca
	v_add_u32_e32 v155, v96, v84
	v_add_u32_e32 v156, v82, v126
	v_mov_b32_e32 v157, v127
	v_mov_b32_e32 v98, 0
	v_mov_b32_e32 v99, v159
	v_mov_b32_e32 v100, v159
	v_mov_b32_e32 v101, v159
	v_mov_b32_e32 v102, 0
	v_mov_b32_e32 v103, v159
	v_mov_b32_e32 v104, v159
	v_mov_b32_e32 v105, v159
	v_mov_b32_e32 v94, 0
	v_mov_b32_e32 v95, v159
	v_mov_b32_e32 v96, v159
	v_mov_b32_e32 v97, v159
	v_mov_b32_e32 v86, 0
	v_mov_b32_e32 v87, v159
	v_mov_b32_e32 v88, v159
	v_mov_b32_e32 v89, v159
	v_mov_b32_e32 v82, 0
	v_mov_b32_e32 v83, v159
	v_mov_b32_e32 v84, v159
	v_mov_b32_e32 v85, v159
	v_mov_b32_e32 v90, 0
	v_mov_b32_e32 v91, v159
	v_mov_b32_e32 v92, v159
	v_mov_b32_e32 v93, v159
	v_mov_b32_e32 v110, 0
	v_mov_b32_e32 v111, v159
	v_mov_b32_e32 v112, v159
	v_mov_b32_e32 v113, v159
	v_mov_b32_e32 v106, 0
	v_mov_b32_e32 v107, v159
	v_mov_b32_e32 v108, v159
	v_mov_b32_e32 v109, v159
.LBB0_928:
	s_add_i32 s0, s24, 1
	s_cmp_ge_i32 s0, s23
	s_cbranch_scc0 .Ldsa_steady
	v_mov_b32_e32 v118, 0
	s_waitcnt vmcnt(13)
	v_dot2_f32_bf16 v118, v26, v26, v118
	v_add_u32_e32 v0, v146, v147
	v_dot2_f32_bf16 v118, v27, v27, v118
	ds_write_b128 v0, v[26:29]
	v_dot2_f32_bf16 v118, v28, v28, v118
	v_add_u32_e32 v0, v146, v148
	v_dot2_f32_bf16 v118, v29, v29, v118
	ds_write_b128 v0, v[18:21]
	v_dot2_f32_bf16 v118, v18, v18, v118
	v_add_u32_e32 v0, v146, v149
	v_dot2_f32_bf16 v118, v19, v19, v118
	ds_write_b128 v0, v[22:25]
	v_dot2_f32_bf16 v118, v20, v20, v118
	v_add_u32_e32 v0, v146, v150
	v_dot2_f32_bf16 v118, v21, v21, v118
	v_and_b32_e32 v119, 64, v206
	v_dot2_f32_bf16 v118, v22, v22, v118
	s_waitcnt vmcnt(12)
	ds_write_b128 v0, v[30:33]
	v_dot2_f32_bf16 v118, v23, v23, v118
	v_dot2_f32_bf16 v118, v24, v24, v118
	v_add_u32_e32 v158, 64, v119
	v_dot2_f32_bf16 v118, v25, v25, v118
	v_dot2_f32_bf16 v118, v30, v30, v118
	v_mfma_f32_16x16x32_bf16 v[114:117], v[2:5], v[26:29], 0
	v_dot2_f32_bf16 v118, v31, v31, v118
	v_dot2_f32_bf16 v118, v32, v32, v118
	v_dot2_f32_bf16 v118, v33, v33, v118
	v_mfma_f32_16x16x32_bf16 v[114:117], v[6:9], v[18:21], v[114:117]
	s_nop 1
	v_mov_b32_e32 v119, v118
	s_nop 1
	v_permlane16_swap_b32_e32 v118, v119
	v_add_f32_e32 v161, v118, v119
	v_xor_b32_e32 v118, 32, v206
	v_mfma_f32_16x16x32_bf16 v[114:117], v[10:13], v[22:25], v[114:117]
	v_cmp_lt_i32_e32 vcc, v118, v158
	s_nop 1
	v_cndmask_b32_e32 v118, v206, v118, vcc
	v_lshlrev_b32_e32 v122, 2, v118
	ds_bpermute_b32 v172, v122, v161
	v_mfma_f32_16x16x32_bf16 v[114:117], v[14:17], v[30:33], v[114:117]
	s_nop 7
	v_cndmask_b32_e64 v114, v114, v115, s[66:67]
	v_cndmask_b32_e64 v114, v114, v116, s[40:41]
	v_cndmask_b32_e64 v114, v114, v117, s[68:69]
	s_nop 1
	v_mov_b32_e32 v115, 0
	s_waitcnt vmcnt(9)
	v_dot2_f32_bf16 v115, v42, v42, v115
	v_mfma_f32_16x16x32_bf16 v[116:119], v[2:5], v[42:45], 0
	v_dot2_f32_bf16 v115, v43, v43, v115
	v_add_u32_e32 v120, v151, v147
	v_dot2_f32_bf16 v115, v44, v44, v115
	ds_write_b128 v120, v[42:45]
	v_dot2_f32_bf16 v115, v45, v45, v115
	v_add_u32_e32 v120, v151, v148
	v_dot2_f32_bf16 v115, v34, v34, v115
	ds_write_b128 v120, v[34:37]
	v_dot2_f32_bf16 v115, v35, v35, v115
	v_add_u32_e32 v120, v151, v149
	v_dot2_f32_bf16 v115, v36, v36, v115
	v_mfma_f32_16x16x32_bf16 v[116:119], v[6:9], v[34:37], v[116:119]
	v_dot2_f32_bf16 v115, v37, v37, v115
	ds_write_b128 v120, v[38:41]
	v_dot2_f32_bf16 v115, v38, v38, v115
	v_add_u32_e32 v120, v151, v150
	v_dot2_f32_bf16 v115, v39, v39, v115
	s_waitcnt vmcnt(8)
	ds_write_b128 v120, v[46:49]
	v_dot2_f32_bf16 v115, v40, v40, v115
	v_mfma_f32_16x16x32_bf16 v[116:119], v[10:13], v[38:41], v[116:119]
	v_dot2_f32_bf16 v115, v41, v41, v115
	v_dot2_f32_bf16 v115, v46, v46, v115
	v_mfma_f32_16x16x32_bf16 v[116:119], v[14:17], v[46:49], v[116:119]
	v_dot2_f32_bf16 v115, v47, v47, v115
	s_nop 0
	v_dot2_f32_bf16 v115, v48, v48, v115
	s_nop 0
	v_dot2_f32_bf16 v115, v49, v49, v115
	s_nop 2
	v_mov_b32_e32 v120, v115
	s_nop 1
	v_permlane16_swap_b32_e32 v115, v120
	v_add_f32_e32 v115, v115, v120
	ds_bpermute_b32 v173, v122, v115
	v_cndmask_b32_e64 v116, v116, v117, s[66:67]
	v_cndmask_b32_e64 v116, v116, v118, s[40:41]
	v_cndmask_b32_e64 v116, v116, v119, s[68:69]
	v_mov_b32_e32 v117, 0
	s_waitcnt vmcnt(5)
; #define LAS __attribute__((address_space(3)))
;     ...
;       auto gl = [&](int b) {
; #pragma unroll
;           for (int jj = 0; jj < 4; ++jj) { const int kx = list[(b * 4 + jj) * 16 + c16] & 4095; const u16* cp = prow + (size_t)kx * NP + C_BC + quad * 8;
; #pragma unroll
;               for (int ks = 0; ks < 4; ++ks) w[jj][ks] = *(const u32x4*)(cp + ks * 32); } };
;       if (nb > 0) gl(0);
;       for (int b = 0; b < nb; ++b) {
;           float lgv[4], rsv[4];
; #pragma unroll
;           for (int jj = 0; jj < 4; ++jj) {
;               const int rho = jj * 16 + c16, slot = b * 64 + rho;
;               f32x4 a = {0.f, 0.f, 0.f, 0.f}; float ss = 0.f;
; #pragma unroll
;               for (int ks = 0; ks < 4; ++ks) {
; #pragma unroll
;                   for (int e = 0; e < 4; ++e) asm("v_dot2_f32_bf16 %0, %1, %1, %0" : "+v"(ss) : "v"(w[jj][ks][e]));
;                   a = __builtin_amdgcn_mfma_f32_16x16x32_bf16(qa[ks], *reinterpret_cast<const bf16x8*>(&w[jj][ks]), a, 0, 0, 0);
;                   *(LAS u32x4*)(wbase + rho * 256 + (((ks * 4 + quad) ^ fsw) << 4)) = w[jj][ks]; }
;               ss += __shfl_xor(ss, 16); ss += __shfl_xor(ss, 32);
;               const float rstd = rsqrtf(ss * (1.f / 128.f) + EPS);
;               const float av = quad == 0 ? a[0] : (quad == 1 ? a[1] : (quad == 2 ? a[2] : a[3]));
;               rsv[jj] = rstd; lgv[jj] = (slot < kcount) ? av * rstd * 0.08838834764831845f : -__builtin_inff();
;           }
;           if (b + 1 < nb) gl(b + 1);
	v_dot2_f32_bf16 v117, v58, v58, v117
	v_mfma_f32_16x16x32_bf16 v[118:121], v[2:5], v[58:61], 0
	v_dot2_f32_bf16 v117, v59, v59, v117
	v_add_u32_e32 v123, v152, v147
	v_dot2_f32_bf16 v117, v60, v60, v117
	ds_write_b128 v123, v[58:61]
	v_dot2_f32_bf16 v117, v61, v61, v117
	v_add_u32_e32 v123, v152, v148
	v_dot2_f32_bf16 v117, v50, v50, v117
	ds_write_b128 v123, v[50:53]
	v_dot2_f32_bf16 v117, v51, v51, v117
	v_add_u32_e32 v123, v152, v149
	v_dot2_f32_bf16 v117, v52, v52, v117
	v_mfma_f32_16x16x32_bf16 v[118:121], v[6:9], v[50:53], v[118:121]
	v_dot2_f32_bf16 v117, v53, v53, v117
	ds_write_b128 v123, v[54:57]
	v_dot2_f32_bf16 v117, v54, v54, v117
	v_add_u32_e32 v123, v152, v150
	v_dot2_f32_bf16 v117, v55, v55, v117
	s_waitcnt vmcnt(4)
	ds_write_b128 v123, v[62:65]
	v_dot2_f32_bf16 v117, v56, v56, v117
	v_mfma_f32_16x16x32_bf16 v[118:121], v[10:13], v[54:57], v[118:121]
	v_dot2_f32_bf16 v117, v57, v57, v117
	v_dot2_f32_bf16 v117, v62, v62, v117
	v_mfma_f32_16x16x32_bf16 v[118:121], v[14:17], v[62:65], v[118:121]
	v_dot2_f32_bf16 v117, v63, v63, v117
	s_nop 0
	v_dot2_f32_bf16 v117, v64, v64, v117
	s_nop 0
	v_dot2_f32_bf16 v117, v65, v65, v117
	s_nop 2
	v_mov_b32_e32 v123, v117
	s_nop 1
	v_permlane16_swap_b32_e32 v117, v123
	v_add_f32_e32 v117, v117, v123
	ds_bpermute_b32 v174, v122, v117
	v_cndmask_b32_e64 v118, v118, v119, s[66:67]
	v_cndmask_b32_e64 v118, v118, v120, s[40:41]
	v_cndmask_b32_e64 v118, v118, v121, s[68:69]
	v_mov_b32_e32 v119, 0
	s_waitcnt vmcnt(1)
	v_dot2_f32_bf16 v119, v74, v74, v119
	v_mfma_f32_16x16x32_bf16 v[176:179], v[2:5], v[74:77], 0
	v_dot2_f32_bf16 v119, v75, v75, v119
	v_add_u32_e32 v120, v153, v147
	v_dot2_f32_bf16 v119, v76, v76, v119
	v_mfma_f32_16x16x32_bf16 v[176:179], v[6:9], v[66:69], v[176:179]
	v_dot2_f32_bf16 v119, v77, v77, v119
	ds_write_b128 v120, v[74:77]
	v_dot2_f32_bf16 v119, v66, v66, v119
	v_mfma_f32_16x16x32_bf16 v[176:179], v[10:13], v[70:73], v[176:179]
	v_dot2_f32_bf16 v119, v67, v67, v119
	v_add_u32_e32 v120, v153, v148
	v_dot2_f32_bf16 v119, v68, v68, v119
	ds_write_b128 v120, v[66:69]
	v_dot2_f32_bf16 v119, v69, v69, v119
	v_add_u32_e32 v120, v153, v149
	v_dot2_f32_bf16 v119, v70, v70, v119
	ds_write_b128 v120, v[70:73]
	v_dot2_f32_bf16 v119, v71, v71, v119
	v_cmp_lt_i32_e32 vcc, 0, v128
	v_dot2_f32_bf16 v119, v72, v72, v119
	s_nop 0
	v_dot2_f32_bf16 v119, v73, v73, v119
	s_waitcnt vmcnt(0)
	v_dot2_f32_bf16 v119, v78, v78, v119
	s_nop 0
	v_dot2_f32_bf16 v119, v79, v79, v119
	s_nop 0
	v_dot2_f32_bf16 v119, v80, v80, v119
	s_nop 0
	v_dot2_f32_bf16 v119, v81, v81, v119
	s_nop 2
	v_mov_b32_e32 v0, v119
	s_nop 1
	v_permlane16_swap_b32_e32 v119, v0
	v_add_f32_e32 v119, v119, v0
	ds_bpermute_b32 v175, v122, v119
	v_mfma_f32_16x16x32_bf16 v[120:123], v[14:17], v[78:81], v[176:179]
	v_add_u32_e32 v0, v153, v150
	ds_write_b128 v0, v[78:81]
	s_nop 5
	v_cndmask_b32_e64 v120, v120, v121, s[66:67]
	v_cndmask_b32_e64 v120, v120, v122, s[40:41]
	v_cndmask_b32_e64 v120, v120, v123, s[68:69]
	s_add_i32 s24, s24, 1
	s_cmp_ge_i32 s24, s23
	s_cbranch_scc1 .LBB0_946
	ds_read_u16 v0, v154
	ds_read_u16 v18, v154 offset:32
	ds_read_u16 v50, v154 offset:64
	ds_read_u16 v51, v154 offset:96
	s_mov_b32 s1, 0x5040100
	s_movk_i32 s20, 0xfff
	s_waitcnt lgkmcnt(2)
	v_perm_b32 v0, v18, v0, s1
	v_and_b32_e32 v18, 0xfff0fff, v0
	v_bitop3_b32 v0, v0, s20, v207 bitop3:0x80
	v_mul_u32_u24_e32 v0, 0x5800, v0
	v_mul_u32_u24_sdwa v34, v18, s33 dst_sel:DWORD dst_unused:UNUSED_PAD src0_sel:WORD_1 src1_sel:DWORD
	v_lshl_add_u64 v[18:19], s[54:55], 0, v[0:1]
	v_mov_b32_e32 v125, v1
	v_lshl_add_u64 v[18:19], v[18:19], 0, v[124:125]
	s_movk_i32 s0, 0x1000
	v_mov_b32_e32 v35, v1
	s_waitcnt lgkmcnt(0)
	v_perm_b32 v0, v51, v50, s1
	v_add_co_u32_e32 v26, vcc, s0, v18
	v_lshl_add_u64 v[34:35], s[54:55], 0, v[34:35]
	v_and_b32_e32 v50, 0xfff0fff, v0
	v_bitop3_b32 v0, v0, s20, v207 bitop3:0x80
	v_addc_co_u32_e32 v27, vcc, 0, v19, vcc
	v_lshl_add_u64 v[34:35], v[34:35], 0, v[124:125]
	v_mul_u32_u24_e32 v0, 0x5800, v0
	v_add_co_u32_e32 v42, vcc, s0, v34
	v_mul_u32_u24_sdwa v66, v50, s33 dst_sel:DWORD dst_unused:UNUSED_PAD src0_sel:WORD_1 src1_sel:DWORD
	v_lshl_add_u64 v[50:51], s[54:55], 0, v[0:1]
	v_addc_co_u32_e32 v43, vcc, 0, v35, vcc
	v_lshl_add_u64 v[50:51], v[50:51], 0, v[124:125]
	v_mov_b32_e32 v67, v1
	v_add_co_u32_e32 v58, vcc, s0, v50
	v_lshl_add_u64 v[66:67], s[54:55], 0, v[66:67]
	s_nop 0
	v_addc_co_u32_e32 v59, vcc, 0, v51, vcc
	v_lshl_add_u64 v[66:67], v[66:67], 0, v[124:125]
	s_mov_b64 s[26:27], 0x1000
	v_add_co_u32_e32 v74, vcc, 0x1000, v66
	v_lshl_add_u64 v[30:31], v[18:19], 0, s[26:27]
	v_lshl_add_u64 v[46:47], v[34:35], 0, s[26:27]
	v_lshl_add_u64 v[62:63], v[50:51], 0, s[26:27]
	v_lshl_add_u64 v[78:79], v[66:67], 0, s[26:27]
	v_addc_co_u32_e32 v75, vcc, 0, v67, vcc
	global_load_dwordx4 v[18:21], v[30:31], off offset:64
	global_load_dwordx4 v[22:25], v[30:31], off offset:128
	s_nop 0
	global_load_dwordx4 v[26:29], v[26:27], off
	s_nop 0
	global_load_dwordx4 v[30:33], v[30:31], off offset:192
	s_nop 0
	global_load_dwordx4 v[34:37], v[46:47], off offset:64
	global_load_dwordx4 v[38:41], v[46:47], off offset:128
	s_nop 0
	global_load_dwordx4 v[42:45], v[42:43], off
	s_nop 0
	global_load_dwordx4 v[46:49], v[46:47], off offset:192
	s_nop 0
	global_load_dwordx4 v[50:53], v[62:63], off offset:64
	global_load_dwordx4 v[54:57], v[62:63], off offset:128
	s_nop 0
	global_load_dwordx4 v[58:61], v[58:59], off
	s_nop 0
	global_load_dwordx4 v[62:65], v[62:63], off offset:192
	s_nop 0
	global_load_dwordx4 v[66:69], v[78:79], off offset:64
	global_load_dwordx4 v[70:73], v[78:79], off offset:128
	s_nop 0
	global_load_dwordx4 v[74:77], v[74:75], off
	s_nop 0
	global_load_dwordx4 v[78:81], v[78:79], off offset:192
; #define LAS __attribute__((address_space(3)))
; __device__ __forceinline__ u16 f2bf(float f) { return (u16)(cvtpk(f, 0.f) & 0xffffu); }
;     ...
;               ss += __shfl_xor(ss, 16); ss += __shfl_xor(ss, 32);
;               const float rstd = rsqrtf(ss * (1.f / 128.f) + EPS);
;               const float av = quad == 0 ? a[0] : (quad == 1 ? a[1] : (quad == 2 ? a[2] : a[3]));
;               rsv[jj] = rstd; lgv[jj] = (slot < kcount) ? av * rstd * 0.08838834764831845f : -__builtin_inff();
;           }
;           if (b + 1 < nb) gl(b + 1);
;           float mx = fmaxf(fmaxf(lgv[0], lgv[1]), fmaxf(lgv[2], lgv[3]));
; #pragma unroll
;           for (int o = 1; o < 16; o <<= 1) mx = fmaxf(mx, __shfl_xor(mx, o));
;           const float mnew = fmaxf(mrun, mx), alpha = __expf(mrun - mnew); mrun = mnew;
;           float ps = 0.f;
; #pragma unroll
;           for (int jj = 0; jj < 4; ++jj) { const float pe = __expf(lgv[jj] - mnew); ps += pe; pbT[quad * 64 + jj * 16 + c16] = f2bf(pe * rsv[jj]); }
;           lsum = lsum * alpha + ps;
;           if (c16 == 0) alf[quad] = alpha;
;           const f32x4 al4 = *(const LAS f32x4*)alf;
; #pragma unroll
;           for (int c = 0; c < 8; ++c) oacc[c] *= al4;
; #pragma unroll
;           for (int ks = 0; ks < 2; ++ks) {
;               const bf16x8 pf = *(const LAS bf16x8*)(pbT + (c16 & 3) * 64 + ks * 32 + quad * 8);
;               u16x4 t0[8], t1[8];
;     ...
;               if (ks == 0) { TRR8(t0, 0, 0); TRR8(t1, 1, 0); } else { TRR8(t0, 0, 8192); TRR8(t1, 1, 8192); }
;     ...
; #pragma unroll
;               for (int c = 0; c < 8; ++c) {
;                   const bf16x8 bf = {(short)t0[c][0], (short)t0[c][1], (short)t0[c][2], (short)t0[c][3], (short)t1[c][0], (short)t1[c][1], (short)t1[c][2], (short)t1[c][3]};
;                   oacc[c] = __builtin_amdgcn_mfma_f32_16x16x32_bf16(pf, bf, oacc[c], 0, 0, 0);
;               }
;           }
.LBB0_946:
	s_waitcnt lgkmcnt(1)
	v_add_f32_e32 v119, v119, v175
	v_add_f32_e32 v117, v117, v174
	v_add_f32_e32 v115, v115, v173
	v_add_f32_e32 v0, v161, v172
	v_fmamk_f32 v119, v119, 0x3c000000, v199
	v_fmamk_f32 v117, v117, 0x3c000000, v199
	v_fmamk_f32 v115, v115, 0x3c000000, v199
	v_fmamk_f32 v0, v0, 0x3c000000, v199
	v_rsq_f32_e32 v122, v119
	v_rsq_f32_e32 v123, v117
	v_rsq_f32_e32 v125, v115
	v_rsq_f32_e32 v161, v0
	v_add_u32_e32 v0, 48, v157
	v_add_u32_e32 v115, 32, v157
	v_mul_f32_e32 v119, v122, v120
	v_cmp_gt_i32_e32 vcc, s22, v0
	v_mul_f32_e32 v117, v123, v118
	v_mul_f32_e32 v119, 0x3db504f3, v119
	v_cndmask_b32_e32 v121, v208, v119, vcc
	v_cmp_gt_i32_e32 vcc, s22, v115
	v_mul_f32_e32 v117, 0x3db504f3, v117
	v_add_u32_e32 v0, 16, v157
	v_cndmask_b32_e32 v120, v208, v117, vcc
	v_mul_f32_e32 v119, v125, v116
	v_cmp_gt_i32_e32 vcc, s22, v0
	v_mul_f32_e32 v119, 0x3db504f3, v119
	v_mul_f32_e32 v0, v161, v114
	v_cndmask_b32_e32 v119, v208, v119, vcc
	v_cmp_gt_i32_e32 vcc, s22, v157
	v_mul_f32_e32 v0, 0x3db504f3, v0
	s_nop 0
	v_cndmask_b32_e32 v118, v208, v0, vcc
	v_max_f32_e32 v0, v120, v121
	v_max3_f32 v114, v118, v119, v0
	s_nop 1
	v_max_f32_dpp v115, v114, v114 quad_perm:[1,0,3,2] row_mask:0xf bank_mask:0xf
	s_nop 1
	v_max_f32_dpp v116, v115, v115 quad_perm:[2,3,0,1] row_mask:0xf bank_mask:0xf
	s_nop 1
	v_max_f32_dpp v117, v116, v116 row_ror:4 row_mask:0xf bank_mask:0xf
	s_nop 1
	v_max_f32_dpp v172, v117, v117 row_ror:8 row_mask:0xf bank_mask:0xf
	v_max3_f32 v117, v160, v117, v172
	v_sub_f32_e32 v118, v118, v117
	v_sub_f32_e32 v119, v119, v117
	v_sub_f32_e32 v120, v120, v117
	v_sub_f32_e32 v121, v121, v117
	v_mul_f32_e32 v118, 0x3fb8aa3b, v118
	v_mul_f32_e32 v119, 0x3fb8aa3b, v119
	v_mul_f32_e32 v120, 0x3fb8aa3b, v120
	v_mul_f32_e32 v121, 0x3fb8aa3b, v121
	v_exp_f32_e32 v118, v118
	v_exp_f32_e32 v119, v119
	v_exp_f32_e32 v120, v120
	v_exp_f32_e32 v121, v121
	v_sub_f32_e32 v160, v160, v117
	v_mul_f32_e32 v161, v161, v118
	v_mul_f32_e32 v125, v125, v119
	v_mul_f32_e32 v123, v123, v120
	v_mul_f32_e32 v122, v122, v121
	v_mul_f32_e32 v160, 0x3fb8aa3b, v160
	v_cvt_pk_bf16_f32 v161, v161, v1
	ds_write_b16 v155, v161 offset:1024
	v_cvt_pk_bf16_f32 v125, v125, v1
	ds_write_b16 v155, v125 offset:1056
	v_cvt_pk_bf16_f32 v123, v123, v1
	ds_write_b16 v155, v123 offset:1088
	v_cvt_pk_bf16_f32 v122, v122, v1
	ds_write_b16 v155, v122 offset:1120
	v_exp_f32_e32 v122, v160
	s_and_saveexec_b64 s[0:1], s[38:39]
	ds_write_b32 v129, v122 offset:640
	s_or_b64 exec, exec, s[0:1]
	v_add_f32_e32 v118, 0, v118
	v_add_f32_e32 v118, v119, v118
	v_add_f32_e32 v118, v120, v118
	v_add_f32_e32 v118, v121, v118
	v_mov_b32_e32 v119, s56
	v_fmac_f32_e32 v118, v159, v122
	ds_read_b128 v[120:123], v119 offset:640
	v_add_u32_e32 v154, 0x80, v154
	v_add_u32_e32 v157, 64, v157
	s_cmp_eq_u32 s23, s24
	s_waitcnt lgkmcnt(0)
	v_pk_mul_f32 v[174:175], v[92:93], v[122:123]
	v_pk_mul_f32 v[172:173], v[90:91], v[120:121]
	v_pk_mul_f32 v[92:93], v[96:97], v[122:123]
	v_pk_mul_f32 v[90:91], v[94:95], v[120:121]
	ds_read_b128 v[94:97], v156 offset:1024
	ds_read_b64_tr_b16 v[216:217], v130 offset:0
	ds_read_b64_tr_b16 v[218:219], v138 offset:0
	ds_read_b64_tr_b16 v[212:213], v131 offset:0
	ds_read_b64_tr_b16 v[214:215], v139 offset:0
	ds_read_b64_tr_b16 v[194:195], v132 offset:0
	ds_read_b64_tr_b16 v[196:197], v140 offset:0
	ds_read_b64_tr_b16 v[190:191], v133 offset:0
	ds_read_b64_tr_b16 v[192:193], v141 offset:0
	ds_read_b64_tr_b16 v[186:187], v134 offset:0
	ds_read_b64_tr_b16 v[188:189], v142 offset:0
	v_pk_mul_f32 v[106:107], v[106:107], v[120:121]
	v_pk_mul_f32 v[110:111], v[110:111], v[120:121]
	v_pk_mul_f32 v[176:177], v[82:83], v[120:121]
	v_pk_mul_f32 v[182:183], v[86:87], v[120:121]
	v_pk_mul_f32 v[86:87], v[102:103], v[120:121]
	v_pk_mul_f32 v[82:83], v[98:99], v[120:121]
	v_pk_mul_f32 v[108:109], v[108:109], v[122:123]
	v_pk_mul_f32 v[112:113], v[112:113], v[122:123]
	v_pk_mul_f32 v[178:179], v[84:85], v[122:123]
	v_pk_mul_f32 v[184:185], v[88:89], v[122:123]
	v_pk_mul_f32 v[88:89], v[104:105], v[122:123]
	v_pk_mul_f32 v[84:85], v[100:101], v[122:123]
	ds_read_b64_tr_b16 v[120:121], v135 offset:0
	ds_read_b64_tr_b16 v[122:123], v143 offset:0
	ds_read_b64_tr_b16 v[102:103], v136 offset:0
	ds_read_b64_tr_b16 v[104:105], v144 offset:0
	s_waitcnt lgkmcnt(12)
	v_mfma_f32_16x16x32_bf16 v[106:109], v[94:97], v[216:219], v[106:109]
	ds_read_b64_tr_b16 v[98:99], v137 offset:0
	ds_read_b64_tr_b16 v[100:101], v145 offset:0
	s_waitcnt lgkmcnt(12)
	v_mfma_f32_16x16x32_bf16 v[110:113], v[94:97], v[212:215], v[110:113]
	s_waitcnt lgkmcnt(10)
	v_mfma_f32_16x16x32_bf16 v[172:175], v[94:97], v[194:197], v[172:175]
	s_waitcnt lgkmcnt(8)
	v_mfma_f32_16x16x32_bf16 v[176:179], v[94:97], v[190:193], v[176:179]
	s_waitcnt lgkmcnt(6)
	v_mfma_f32_16x16x32_bf16 v[182:185], v[94:97], v[186:189], v[182:185]
	s_waitcnt lgkmcnt(4)
	v_mfma_f32_16x16x32_bf16 v[120:123], v[94:97], v[120:123], v[90:93]
	s_waitcnt lgkmcnt(2)
	v_mfma_f32_16x16x32_bf16 v[102:105], v[94:97], v[102:105], v[86:89]
	s_waitcnt lgkmcnt(0)
	v_mfma_f32_16x16x32_bf16 v[98:101], v[94:97], v[98:101], v[82:85]
	ds_read_b128 v[220:223], v156 offset:1088
	ds_read_b64_tr_b16 v[212:213], v130 offset:8192
	ds_read_b64_tr_b16 v[214:215], v138 offset:8192
	ds_read_b64_tr_b16 v[194:195], v131 offset:8192
	ds_read_b64_tr_b16 v[196:197], v139 offset:8192
	ds_read_b64_tr_b16 v[90:91], v132 offset:8192
	ds_read_b64_tr_b16 v[92:93], v140 offset:8192
	ds_read_b64_tr_b16 v[82:83], v133 offset:8192
	ds_read_b64_tr_b16 v[84:85], v141 offset:8192
	ds_read_b64_tr_b16 v[86:87], v134 offset:8192
	ds_read_b64_tr_b16 v[88:89], v142 offset:8192
	ds_read_b64_tr_b16 v[94:95], v135 offset:8192
	ds_read_b64_tr_b16 v[96:97], v143 offset:8192
	ds_read_b64_tr_b16 v[190:191], v136 offset:8192
	ds_read_b64_tr_b16 v[192:193], v144 offset:8192
	s_waitcnt lgkmcnt(12)
	v_mfma_f32_16x16x32_bf16 v[106:109], v[220:223], v[212:215], v[106:109]
	ds_read_b64_tr_b16 v[186:187], v137 offset:8192
	ds_read_b64_tr_b16 v[188:189], v145 offset:8192
	s_waitcnt lgkmcnt(12)
	v_mfma_f32_16x16x32_bf16 v[110:113], v[220:223], v[194:197], v[110:113]
	s_waitcnt lgkmcnt(10)
	v_mfma_f32_16x16x32_bf16 v[90:93], v[220:223], v[90:93], v[172:175]
	s_waitcnt lgkmcnt(8)
	v_mfma_f32_16x16x32_bf16 v[82:85], v[220:223], v[82:85], v[176:179]
	s_waitcnt lgkmcnt(6)
	v_mfma_f32_16x16x32_bf16 v[86:89], v[220:223], v[86:89], v[182:185]
	s_waitcnt lgkmcnt(4)
	v_mfma_f32_16x16x32_bf16 v[94:97], v[220:223], v[94:97], v[120:123]
	s_waitcnt lgkmcnt(2)
	v_mfma_f32_16x16x32_bf16 v[102:105], v[220:223], v[190:193], v[102:105]
	s_waitcnt lgkmcnt(0)
	v_mfma_f32_16x16x32_bf16 v[98:101], v[220:223], v[186:189], v[98:101]
	s_cbranch_scc1 .LBB0_952
	v_mov_b32_e32 v159, v118
	v_mov_b32_e32 v160, v117
	s_branch .LBB0_928
; #define LAS __attribute__((address_space(3)))
;     ...
;       auto gl = [&](int b) {
; #pragma unroll
;           for (int jj = 0; jj < 4; ++jj) { const int kx = list[(b * 4 + jj) * 16 + c16] & 4095; const u16* cp = prow + (size_t)kx * NP + C_BC + quad * 8;
; #pragma unroll
;               for (int ks = 0; ks < 4; ++ks) w[jj][ks] = *(const u32x4*)(cp + ks * 32); } };
;       if (nb > 0) gl(0);
;       for (int b = 0; b < nb; ++b) {
;           float lgv[4], rsv[4];
; #pragma unroll
;           for (int jj = 0; jj < 4; ++jj) {
;               const int rho = jj * 16 + c16, slot = b * 64 + rho;
;               f32x4 a = {0.f, 0.f, 0.f, 0.f}; float ss = 0.f;
; #pragma unroll
;               for (int ks = 0; ks < 4; ++ks) {
; #pragma unroll
;                   for (int e = 0; e < 4; ++e) asm("v_dot2_f32_bf16 %0, %1, %1, %0" : "+v"(ss) : "v"(w[jj][ks][e]));
;                   a = __builtin_amdgcn_mfma_f32_16x16x32_bf16(qa[ks], *reinterpret_cast<const bf16x8*>(&w[jj][ks]), a, 0, 0, 0);
;                   *(LAS u32x4*)(wbase + rho * 256 + (((ks * 4 + quad) ^ fsw) << 4)) = w[jj][ks]; }
;               ss += __shfl_xor(ss, 16); ss += __shfl_xor(ss, 32);
;               const float rstd = rsqrtf(ss * (1.f / 128.f) + EPS);
;               const float av = quad == 0 ? a[0] : (quad == 1 ? a[1] : (quad == 2 ? a[2] : a[3]));
.Ldsa_steady:
	ds_read_u16 v232, v154
	ds_read_u16 v234, v154 offset:32
	ds_read_u16 v236, v154 offset:64
	ds_read_u16 v238, v154 offset:96
	v_mov_b32_e32 v240, v124
	v_mov_b32_e32 v241, 0
	v_mov_b32_e32 v233, 0
	v_mov_b32_e32 v235, 0
	v_mov_b32_e32 v237, 0
	v_mov_b32_e32 v239, 0
	s_mov_b64 s[0:1], 0x1000
	v_lshl_add_u64 v[242:243], s[54:55], 0, v[240:241]
	v_lshl_add_u64 v[242:243], v[242:243], 0, s[0:1]
	s_waitcnt lgkmcnt(0)
	v_and_b32_e32 v232, 0xfff, v232
	v_mul_u32_u24_e32 v232, 0x5800, v232
	v_lshl_add_u64 v[224:225], v[232:233], 0, v[242:243]
	v_and_b32_e32 v234, 0xfff, v234
	v_mul_u32_u24_e32 v234, 0x5800, v234
	v_lshl_add_u64 v[226:227], v[234:235], 0, v[242:243]
	v_and_b32_e32 v236, 0xfff, v236
	v_mul_u32_u24_e32 v236, 0x5800, v236
	v_lshl_add_u64 v[228:229], v[236:237], 0, v[242:243]
	v_and_b32_e32 v238, 0xfff, v238
	v_mul_u32_u24_e32 v238, 0x5800, v238
	v_lshl_add_u64 v[230:231], v[238:239], 0, v[242:243]
	v_mov_b32_e32 v118, 0
	s_waitcnt vmcnt(13)
	v_dot2_f32_bf16 v118, v26, v26, v118
	v_add_u32_e32 v0, v146, v147
	v_dot2_f32_bf16 v118, v27, v27, v118
	ds_write_b128 v0, v[26:29]
	v_dot2_f32_bf16 v118, v28, v28, v118
	v_add_u32_e32 v0, v146, v148
	v_dot2_f32_bf16 v118, v29, v29, v118
	ds_write_b128 v0, v[18:21]
	v_dot2_f32_bf16 v118, v18, v18, v118
	v_add_u32_e32 v0, v146, v149
	v_dot2_f32_bf16 v118, v19, v19, v118
	ds_write_b128 v0, v[22:25]
	v_dot2_f32_bf16 v118, v20, v20, v118
	v_add_u32_e32 v0, v146, v150
	v_dot2_f32_bf16 v118, v21, v21, v118
	v_and_b32_e32 v119, 64, v206
	v_dot2_f32_bf16 v118, v22, v22, v118
	s_waitcnt vmcnt(12)
	ds_write_b128 v0, v[30:33]
	v_dot2_f32_bf16 v118, v23, v23, v118
	v_dot2_f32_bf16 v118, v24, v24, v118
	v_add_u32_e32 v158, 64, v119
	v_dot2_f32_bf16 v118, v25, v25, v118
	v_dot2_f32_bf16 v118, v30, v30, v118
	v_mfma_f32_16x16x32_bf16 v[114:117], v[2:5], v[26:29], 0
	v_dot2_f32_bf16 v118, v31, v31, v118
	v_dot2_f32_bf16 v118, v32, v32, v118
	v_dot2_f32_bf16 v118, v33, v33, v118
	v_mfma_f32_16x16x32_bf16 v[114:117], v[6:9], v[18:21], v[114:117]
	s_nop 1
	v_mov_b32_e32 v119, v118
	s_nop 1
	v_permlane16_swap_b32_e32 v118, v119
	v_add_f32_e32 v161, v118, v119
	v_xor_b32_e32 v118, 32, v206
	v_mfma_f32_16x16x32_bf16 v[114:117], v[10:13], v[22:25], v[114:117]
	v_cmp_lt_i32_e32 vcc, v118, v158
	s_nop 1
	v_cndmask_b32_e32 v118, v206, v118, vcc
	v_lshlrev_b32_e32 v122, 2, v118
	ds_bpermute_b32 v172, v122, v161
	v_mfma_f32_16x16x32_bf16 v[114:117], v[14:17], v[30:33], v[114:117]
	global_load_dwordx4 v[18:21], v[224:225], off offset:64
	global_load_dwordx4 v[22:25], v[224:225], off offset:128
	global_load_dwordx4 v[26:29], v[224:225], off
	global_load_dwordx4 v[30:33], v[224:225], off offset:192
	s_nop 3
	v_cndmask_b32_e64 v114, v114, v115, s[66:67]
	v_cndmask_b32_e64 v114, v114, v116, s[40:41]
	v_cndmask_b32_e64 v114, v114, v117, s[68:69]
	s_nop 1
	v_mov_b32_e32 v115, 0
	s_waitcnt vmcnt(13)
	v_dot2_f32_bf16 v115, v42, v42, v115
	v_mfma_f32_16x16x32_bf16 v[116:119], v[2:5], v[42:45], 0
	v_dot2_f32_bf16 v115, v43, v43, v115
	v_add_u32_e32 v120, v151, v147
	v_dot2_f32_bf16 v115, v44, v44, v115
	ds_write_b128 v120, v[42:45]
	v_dot2_f32_bf16 v115, v45, v45, v115
	v_add_u32_e32 v120, v151, v148
	v_dot2_f32_bf16 v115, v34, v34, v115
	ds_write_b128 v120, v[34:37]
	v_dot2_f32_bf16 v115, v35, v35, v115
	v_add_u32_e32 v120, v151, v149
	v_dot2_f32_bf16 v115, v36, v36, v115
	v_mfma_f32_16x16x32_bf16 v[116:119], v[6:9], v[34:37], v[116:119]
	v_dot2_f32_bf16 v115, v37, v37, v115
	ds_write_b128 v120, v[38:41]
	v_dot2_f32_bf16 v115, v38, v38, v115
	v_add_u32_e32 v120, v151, v150
	v_dot2_f32_bf16 v115, v39, v39, v115
	s_waitcnt vmcnt(12)
; #define LAS __attribute__((address_space(3)))
;     ...
;           for (int jj = 0; jj < 4; ++jj) {
;               const int rho = jj * 16 + c16, slot = b * 64 + rho;
;               f32x4 a = {0.f, 0.f, 0.f, 0.f}; float ss = 0.f;
; #pragma unroll
;               for (int ks = 0; ks < 4; ++ks) {
; #pragma unroll
;                   for (int e = 0; e < 4; ++e) asm("v_dot2_f32_bf16 %0, %1, %1, %0" : "+v"(ss) : "v"(w[jj][ks][e]));
;                   a = __builtin_amdgcn_mfma_f32_16x16x32_bf16(qa[ks], *reinterpret_cast<const bf16x8*>(&w[jj][ks]), a, 0, 0, 0);
;                   *(LAS u32x4*)(wbase + rho * 256 + (((ks * 4 + quad) ^ fsw) << 4)) = w[jj][ks]; }
;               ss += __shfl_xor(ss, 16); ss += __shfl_xor(ss, 32);
;               const float rstd = rsqrtf(ss * (1.f / 128.f) + EPS);
;               const float av = quad == 0 ? a[0] : (quad == 1 ? a[1] : (quad == 2 ? a[2] : a[3]));
;               rsv[jj] = rstd; lgv[jj] = (slot < kcount) ? av * rstd * 0.08838834764831845f : -__builtin_inff();
;           }
;           if (b + 1 < nb) gl(b + 1);
	ds_write_b128 v120, v[46:49]
	v_dot2_f32_bf16 v115, v40, v40, v115
	v_mfma_f32_16x16x32_bf16 v[116:119], v[10:13], v[38:41], v[116:119]
	v_dot2_f32_bf16 v115, v41, v41, v115
	v_dot2_f32_bf16 v115, v46, v46, v115
	v_mfma_f32_16x16x32_bf16 v[116:119], v[14:17], v[46:49], v[116:119]
	v_dot2_f32_bf16 v115, v47, v47, v115
	s_nop 0
	v_dot2_f32_bf16 v115, v48, v48, v115
	s_nop 0
	v_dot2_f32_bf16 v115, v49, v49, v115
	global_load_dwordx4 v[34:37], v[226:227], off offset:64
	global_load_dwordx4 v[38:41], v[226:227], off offset:128
	global_load_dwordx4 v[42:45], v[226:227], off
	global_load_dwordx4 v[46:49], v[226:227], off offset:192
	s_nop 2
	v_mov_b32_e32 v120, v115
	s_nop 1
	v_permlane16_swap_b32_e32 v115, v120
	v_add_f32_e32 v115, v115, v120
	ds_bpermute_b32 v173, v122, v115
	v_cndmask_b32_e64 v116, v116, v117, s[66:67]
	v_cndmask_b32_e64 v116, v116, v118, s[40:41]
	v_cndmask_b32_e64 v116, v116, v119, s[68:69]
	v_mov_b32_e32 v117, 0
	s_waitcnt vmcnt(13)
	v_dot2_f32_bf16 v117, v58, v58, v117
	v_mfma_f32_16x16x32_bf16 v[118:121], v[2:5], v[58:61], 0
	v_dot2_f32_bf16 v117, v59, v59, v117
	v_add_u32_e32 v123, v152, v147
	v_dot2_f32_bf16 v117, v60, v60, v117
	ds_write_b128 v123, v[58:61]
	v_dot2_f32_bf16 v117, v61, v61, v117
	v_add_u32_e32 v123, v152, v148
	v_dot2_f32_bf16 v117, v50, v50, v117
	ds_write_b128 v123, v[50:53]
	v_dot2_f32_bf16 v117, v51, v51, v117
	v_add_u32_e32 v123, v152, v149
	v_dot2_f32_bf16 v117, v52, v52, v117
	v_mfma_f32_16x16x32_bf16 v[118:121], v[6:9], v[50:53], v[118:121]
	v_dot2_f32_bf16 v117, v53, v53, v117
	ds_write_b128 v123, v[54:57]
	v_dot2_f32_bf16 v117, v54, v54, v117
	v_add_u32_e32 v123, v152, v150
	v_dot2_f32_bf16 v117, v55, v55, v117
	s_waitcnt vmcnt(12)
	ds_write_b128 v123, v[62:65]
	v_dot2_f32_bf16 v117, v56, v56, v117
	v_mfma_f32_16x16x32_bf16 v[118:121], v[10:13], v[54:57], v[118:121]
	v_dot2_f32_bf16 v117, v57, v57, v117
	v_dot2_f32_bf16 v117, v62, v62, v117
	v_mfma_f32_16x16x32_bf16 v[118:121], v[14:17], v[62:65], v[118:121]
	v_dot2_f32_bf16 v117, v63, v63, v117
	s_nop 0
	v_dot2_f32_bf16 v117, v64, v64, v117
	s_nop 0
	v_dot2_f32_bf16 v117, v65, v65, v117
	global_load_dwordx4 v[50:53], v[228:229], off offset:64
	global_load_dwordx4 v[54:57], v[228:229], off offset:128
	global_load_dwordx4 v[58:61], v[228:229], off
	global_load_dwordx4 v[62:65], v[228:229], off offset:192
	s_nop 2
	v_mov_b32_e32 v123, v117
	s_nop 1
	v_permlane16_swap_b32_e32 v117, v123
	v_add_f32_e32 v117, v117, v123
	ds_bpermute_b32 v174, v122, v117
	v_cndmask_b32_e64 v118, v118, v119, s[66:67]
	v_cndmask_b32_e64 v118, v118, v120, s[40:41]
	v_cndmask_b32_e64 v118, v118, v121, s[68:69]
	v_mov_b32_e32 v119, 0
	s_waitcnt vmcnt(13)
	v_dot2_f32_bf16 v119, v74, v74, v119
	v_mfma_f32_16x16x32_bf16 v[176:179], v[2:5], v[74:77], 0
	v_dot2_f32_bf16 v119, v75, v75, v119
	v_add_u32_e32 v120, v153, v147
	v_dot2_f32_bf16 v119, v76, v76, v119
	v_mfma_f32_16x16x32_bf16 v[176:179], v[6:9], v[66:69], v[176:179]
	v_dot2_f32_bf16 v119, v77, v77, v119
	ds_write_b128 v120, v[74:77]
	v_dot2_f32_bf16 v119, v66, v66, v119
	v_mfma_f32_16x16x32_bf16 v[176:179], v[10:13], v[70:73], v[176:179]
	v_dot2_f32_bf16 v119, v67, v67, v119
	v_add_u32_e32 v120, v153, v148
	v_dot2_f32_bf16 v119, v68, v68, v119
	ds_write_b128 v120, v[66:69]
	v_dot2_f32_bf16 v119, v69, v69, v119
	v_add_u32_e32 v120, v153, v149
	v_dot2_f32_bf16 v119, v70, v70, v119
	ds_write_b128 v120, v[70:73]
	v_dot2_f32_bf16 v119, v71, v71, v119
	v_cmp_lt_i32_e32 vcc, 0, v128
	v_dot2_f32_bf16 v119, v72, v72, v119
	s_nop 0
	v_dot2_f32_bf16 v119, v73, v73, v119
	s_waitcnt vmcnt(12)
	v_dot2_f32_bf16 v119, v78, v78, v119
	s_nop 0
	v_dot2_f32_bf16 v119, v79, v79, v119
	s_nop 0
	v_dot2_f32_bf16 v119, v80, v80, v119
	s_nop 0
	v_dot2_f32_bf16 v119, v81, v81, v119
	s_nop 2
	v_mov_b32_e32 v0, v119
	s_nop 1
	v_permlane16_swap_b32_e32 v119, v0
	v_add_f32_e32 v119, v119, v0
	ds_bpermute_b32 v175, v122, v119
	v_mfma_f32_16x16x32_bf16 v[120:123], v[14:17], v[78:81], v[176:179]
	v_add_u32_e32 v0, v153, v150
	ds_write_b128 v0, v[78:81]
	global_load_dwordx4 v[66:69], v[230:231], off offset:64
	global_load_dwordx4 v[70:73], v[230:231], off offset:128
	global_load_dwordx4 v[74:77], v[230:231], off
	global_load_dwordx4 v[78:81], v[230:231], off offset:192
	s_nop 1
	v_cndmask_b32_e64 v120, v120, v121, s[66:67]
	v_cndmask_b32_e64 v120, v120, v122, s[40:41]
	v_cndmask_b32_e64 v120, v120, v123, s[68:69]
	s_add_i32 s24, s24, 1
	s_branch .LBB0_946
